# wave_sum cross-row step via row_bcast DPP + readlane instead of two ds_bpermute round trips (rwkv_fin, rwkv_prep)
# speedup vs baseline: 1.0053x; 1.0053x over previous
; __device__ __forceinline__ unsigned short f2bf(float f) { unsigned r; asm("v_cvt_pk_bf16_f32 %0, %1, %1" : "=v"(r) : "v"(f)); return (unsigned short)(r & 0xffffu); }
; __device__ __forceinline__ float wave_sum(float v) {
;   v = row16_sum(v); v += __shfl_xor(v, 16); v += __shfl_xor(v, 32);
;   return v;
; }
; __device__ __forceinline__ void rwkv_fin_item(const Params& p, int l, int item, char* ldsraw) {
;     ...
; #pragma unroll
;   for (int t = 0; t < 16; t++) {
;     const float y = yv[t];
;     const float mean = wave_sum(y) * (1.f / 64.f);
;     const float dlt = y - mean;
;     const float var = wave_sum(dlt * dlt) * (1.f / 64.f);
;     const float yn = dlt * rsqrtf(var + 64e-5f) * lw + lb;
;     const float g = lds[1024 + t * 256 + tid];
;     Y[(size_t)(tok0 + t) * 1024 + 512 + tid] = f2bf((yn + c3v[t] * vv[t]) * g);
;   }
.LBB0_139:
	v_and_b32_e32 v48, 64, v218
	v_lshlrev_b32_e32 v55, 16, v87
	v_lshlrev_b32_e32 v87, 16, v76
	v_xor_b32_e32 v2, 16, v218
	v_add_u32_e32 v76, 64, v48
	v_cmp_lt_i32_e32 vcc, v2, v76
	v_lshlrev_b32_e32 v57, 16, v86
	v_lshlrev_b32_e32 v86, 16, v77
	v_cndmask_b32_e32 v2, v218, v2, vcc
	v_lshlrev_b32_e32 v48, 2, v2
	v_xor_b32_e32 v2, 32, v218
	v_cmp_lt_i32_e32 vcc, v2, v76
	v_add_f32_dpp v76, v52, v52 quad_perm:[1,0,3,2] row_mask:0xf bank_mask:0xf bound_ctrl:1
	v_lshlrev_b32_e32 v75, 16, v75
	v_cndmask_b32_e32 v2, v218, v2, vcc
	v_add_f32_dpp v76, v76, v76 quad_perm:[2,3,0,1] row_mask:0xf bank_mask:0xf bound_ctrl:1
	v_lshlrev_b32_e32 v2, 2, v2
	v_lshlrev_b32_e32 v78, 16, v78
	v_add_f32_dpp v76, v76, v76 row_ror:4 row_mask:0xf bank_mask:0xf bound_ctrl:1
	v_lshlrev_b32_e32 v79, 16, v79
	v_lshlrev_b32_e32 v80, 16, v80
	v_add_f32_dpp v76, v76, v76 row_ror:8 row_mask:0xf bank_mask:0xf bound_ctrl:1
	ds_bpermute_b32 v77, v48, v76
	v_lshlrev_b32_e32 v81, 16, v81
	v_lshlrev_b32_e32 v82, 16, v82
	v_lshlrev_b32_e32 v83, 16, v83
	v_lshlrev_b32_e32 v84, 16, v84
	s_waitcnt lgkmcnt(0)
	v_add_f32_e32 v76, v76, v77
	ds_bpermute_b32 v77, v2, v76
	v_lshlrev_b32_e32 v85, 16, v85
	v_lshlrev_b32_e32 v54, 16, v88
	v_lshlrev_b32_e32 v49, 16, v89
	s_waitcnt vmcnt(1)
	v_lshlrev_b32_e32 v0, 16, v90
	s_waitcnt lgkmcnt(0)
	v_add_f32_e32 v76, v76, v77
	v_fmamk_f32 v52, v76, 0xbc800000, v52
	v_mul_f32_e32 v76, v52, v52
	s_add_i32 s31, s31, s77
	s_cmpk_gt_i32 s31, 0x3ff
	v_mov_b32_dpp v76, v76 quad_perm:[1,0,3,2] row_mask:0xf bank_mask:0xf bound_ctrl:1
	v_fmac_f32_e32 v76, v52, v52
	s_nop 1
	v_add_f32_dpp v76, v76, v76 quad_perm:[2,3,0,1] row_mask:0xf bank_mask:0xf bound_ctrl:1
	s_nop 1
	v_add_f32_dpp v76, v76, v76 row_ror:4 row_mask:0xf bank_mask:0xf bound_ctrl:1
	s_nop 1
	v_add_f32_dpp v76, v76, v76 row_ror:8 row_mask:0xf bank_mask:0xf bound_ctrl:1
	s_nop 1
	v_add_f32_dpp v76, v76, v76 row_bcast:15 row_mask:0xa bank_mask:0xf
	s_nop 1
	v_add_f32_dpp v76, v76, v76 row_bcast:31 row_mask:0xc bank_mask:0xf
	s_nop 0
	v_readlane_b32 vcc_lo, v76, 63
	s_nop 1
	v_mov_b32_e32 v76, vcc_lo
	v_fmamk_f32 v76, v76, 0x3c800000, v201
	v_cmp_gt_f32_e32 vcc, s83, v76
	v_mul_f32_e32 v77, 0x4b800000, v76
	s_nop 0
	v_cndmask_b32_e32 v76, v76, v77, vcc
	v_rsq_f32_e32 v76, v76
	s_nop 0
	v_mul_f32_e32 v77, 0x45800000, v76
	v_cndmask_b32_e32 v76, v76, v77, vcc
	v_mul_f32_e32 v52, v52, v76
	ds_read2st64_b32 v[76:77], v56 offset0:16 offset1:20
	v_fma_f32 v52, v58, v52, v59
	v_fmac_f32_e32 v52, v74, v75
	s_waitcnt lgkmcnt(0)
	v_mul_f32_e32 v52, v76, v52
	v_cvt_pk_bf16_f32 v52, v52, v52
	global_store_short v[42:43], v52, off offset:1024
	v_add_f32_dpp v42, v53, v53 quad_perm:[1,0,3,2] row_mask:0xf bank_mask:0xf bound_ctrl:1
	s_nop 1
	v_add_f32_dpp v42, v42, v42 quad_perm:[2,3,0,1] row_mask:0xf bank_mask:0xf bound_ctrl:1
	s_nop 1
	v_add_f32_dpp v42, v42, v42 row_ror:4 row_mask:0xf bank_mask:0xf bound_ctrl:1
	s_nop 1
	v_add_f32_dpp v42, v42, v42 row_ror:8 row_mask:0xf bank_mask:0xf bound_ctrl:1
	s_nop 1
	v_add_f32_dpp v42, v42, v42 row_bcast:15 row_mask:0xa bank_mask:0xf
	s_nop 1
	v_add_f32_dpp v42, v42, v42 row_bcast:31 row_mask:0xc bank_mask:0xf
	s_nop 0
	v_readlane_b32 vcc_lo, v42, 63
	s_nop 1
	v_mov_b32_e32 v42, vcc_lo
	v_fmac_f32_e32 v53, 0xbc800000, v42
	v_mul_f32_e32 v42, v53, v53
	s_nop 1
	v_mov_b32_dpp v42, v42 quad_perm:[1,0,3,2] row_mask:0xf bank_mask:0xf bound_ctrl:1
	v_fmac_f32_e32 v42, v53, v53
	s_nop 1
	v_add_f32_dpp v42, v42, v42 quad_perm:[2,3,0,1] row_mask:0xf bank_mask:0xf bound_ctrl:1
	s_nop 1
	v_add_f32_dpp v42, v42, v42 row_ror:4 row_mask:0xf bank_mask:0xf bound_ctrl:1
	s_nop 1
	v_add_f32_dpp v42, v42, v42 row_ror:8 row_mask:0xf bank_mask:0xf bound_ctrl:1
	s_nop 1
	v_add_f32_dpp v42, v42, v42 row_bcast:15 row_mask:0xa bank_mask:0xf
	s_nop 1
	v_add_f32_dpp v42, v42, v42 row_bcast:31 row_mask:0xc bank_mask:0xf
	s_nop 0
	v_readlane_b32 vcc_lo, v42, 63
	s_nop 1
	v_mov_b32_e32 v42, vcc_lo
	v_fmamk_f32 v42, v42, 0x3c800000, v201
	v_cmp_gt_f32_e32 vcc, s83, v42
	v_mul_f32_e32 v43, 0x4b800000, v42
	s_nop 0
	v_cndmask_b32_e32 v42, v42, v43, vcc
	v_rsq_f32_e32 v42, v42
	s_nop 0
	v_mul_f32_e32 v43, 0x45800000, v42
	v_cndmask_b32_e32 v42, v42, v43, vcc
	v_mul_f32_e32 v42, v53, v42
	v_fma_f32 v42, v58, v42, v59
	v_fmac_f32_e32 v42, v73, v87
	v_mul_f32_e32 v42, v77, v42
	v_cvt_pk_bf16_f32 v42, v42, v42
	global_store_short v[40:41], v42, off offset:1024
	v_add_f32_dpp v40, v50, v50 quad_perm:[1,0,3,2] row_mask:0xf bank_mask:0xf bound_ctrl:1
	s_nop 1
	v_add_f32_dpp v40, v40, v40 quad_perm:[2,3,0,1] row_mask:0xf bank_mask:0xf bound_ctrl:1
	s_nop 1
	v_add_f32_dpp v40, v40, v40 row_ror:4 row_mask:0xf bank_mask:0xf bound_ctrl:1
	s_nop 1
	v_add_f32_dpp v40, v40, v40 row_ror:8 row_mask:0xf bank_mask:0xf bound_ctrl:1
	s_nop 1
	v_add_f32_dpp v40, v40, v40 row_bcast:15 row_mask:0xa bank_mask:0xf
	s_nop 1
	v_add_f32_dpp v40, v40, v40 row_bcast:31 row_mask:0xc bank_mask:0xf
	s_nop 0
	v_readlane_b32 vcc_lo, v40, 63
	s_nop 1
	v_mov_b32_e32 v40, vcc_lo
	v_fmamk_f32 v40, v40, 0xbc800000, v50
	v_mul_f32_e32 v41, v40, v40
	s_nop 1
	v_mov_b32_dpp v41, v41 quad_perm:[1,0,3,2] row_mask:0xf bank_mask:0xf bound_ctrl:1
	v_fmac_f32_e32 v41, v40, v40
	s_nop 1
	v_add_f32_dpp v41, v41, v41 quad_perm:[2,3,0,1] row_mask:0xf bank_mask:0xf bound_ctrl:1
	s_nop 1
	v_add_f32_dpp v41, v41, v41 row_ror:4 row_mask:0xf bank_mask:0xf bound_ctrl:1
	s_nop 1
	v_add_f32_dpp v41, v41, v41 row_ror:8 row_mask:0xf bank_mask:0xf bound_ctrl:1
	s_nop 1
	v_add_f32_dpp v41, v41, v41 row_bcast:15 row_mask:0xa bank_mask:0xf
	s_nop 1
	v_add_f32_dpp v41, v41, v41 row_bcast:31 row_mask:0xc bank_mask:0xf
	s_nop 0
	v_readlane_b32 vcc_lo, v41, 63
	s_nop 1
	v_mov_b32_e32 v41, vcc_lo
	v_fmamk_f32 v41, v41, 0x3c800000, v201
	v_cmp_gt_f32_e32 vcc, s83, v41
	v_mul_f32_e32 v42, 0x4b800000, v41
	s_nop 0
	v_cndmask_b32_e32 v41, v41, v42, vcc
	v_rsq_f32_e32 v41, v41
	s_nop 0
	v_mul_f32_e32 v42, 0x45800000, v41
	v_cndmask_b32_e32 v41, v41, v42, vcc
	v_mul_f32_e32 v40, v40, v41
	v_fma_f32 v42, v58, v40, v59
	ds_read2st64_b32 v[40:41], v56 offset0:24 offset1:28
	v_fmac_f32_e32 v42, v72, v86
	s_waitcnt lgkmcnt(0)
; __device__ __forceinline__ unsigned short f2bf(float f) { unsigned r; asm("v_cvt_pk_bf16_f32 %0, %1, %1" : "=v"(r) : "v"(f)); return (unsigned short)(r & 0xffffu); }
; __device__ __forceinline__ float wave_sum(float v) {
;   v = row16_sum(v); v += __shfl_xor(v, 16); v += __shfl_xor(v, 32);
;   return v;
; }
; __device__ __forceinline__ void rwkv_fin_item(const Params& p, int l, int item, char* ldsraw) {
;     ...
; #pragma unroll
;   for (int t = 0; t < 16; t++) {
;     const float y = yv[t];
;     const float mean = wave_sum(y) * (1.f / 64.f);
;     const float dlt = y - mean;
;     const float var = wave_sum(dlt * dlt) * (1.f / 64.f);
;     const float yn = dlt * rsqrtf(var + 64e-5f) * lw + lb;
;     const float g = lds[1024 + t * 256 + tid];
;     Y[(size_t)(tok0 + t) * 1024 + 512 + tid] = f2bf((yn + c3v[t] * vv[t]) * g);
;   }
	v_mul_f32_e32 v40, v40, v42
	v_cvt_pk_bf16_f32 v40, v40, v40
	global_store_short v[38:39], v40, off offset:1024
	v_add_f32_dpp v38, v51, v51 quad_perm:[1,0,3,2] row_mask:0xf bank_mask:0xf bound_ctrl:1
	s_nop 1
	v_add_f32_dpp v38, v38, v38 quad_perm:[2,3,0,1] row_mask:0xf bank_mask:0xf bound_ctrl:1
	s_nop 1
	v_add_f32_dpp v38, v38, v38 row_ror:4 row_mask:0xf bank_mask:0xf bound_ctrl:1
	s_nop 1
	v_add_f32_dpp v38, v38, v38 row_ror:8 row_mask:0xf bank_mask:0xf bound_ctrl:1
	s_nop 1
	v_add_f32_dpp v38, v38, v38 row_bcast:15 row_mask:0xa bank_mask:0xf
	s_nop 1
	v_add_f32_dpp v38, v38, v38 row_bcast:31 row_mask:0xc bank_mask:0xf
	s_nop 0
	v_readlane_b32 vcc_lo, v38, 63
	s_nop 1
	v_mov_b32_e32 v38, vcc_lo
	v_fmac_f32_e32 v51, 0xbc800000, v38
	v_mul_f32_e32 v38, v51, v51
	s_nop 1
	v_mov_b32_dpp v38, v38 quad_perm:[1,0,3,2] row_mask:0xf bank_mask:0xf bound_ctrl:1
	v_fmac_f32_e32 v38, v51, v51
	s_nop 1
	v_add_f32_dpp v38, v38, v38 quad_perm:[2,3,0,1] row_mask:0xf bank_mask:0xf bound_ctrl:1
	s_nop 1
	v_add_f32_dpp v38, v38, v38 row_ror:4 row_mask:0xf bank_mask:0xf bound_ctrl:1
	s_nop 1
	v_add_f32_dpp v38, v38, v38 row_ror:8 row_mask:0xf bank_mask:0xf bound_ctrl:1
	s_nop 1
	v_add_f32_dpp v38, v38, v38 row_bcast:15 row_mask:0xa bank_mask:0xf
	s_nop 1
	v_add_f32_dpp v38, v38, v38 row_bcast:31 row_mask:0xc bank_mask:0xf
	s_nop 0
	v_readlane_b32 vcc_lo, v38, 63
	s_nop 1
	v_mov_b32_e32 v38, vcc_lo
	v_fmamk_f32 v38, v38, 0x3c800000, v201
	v_cmp_gt_f32_e32 vcc, s83, v38
	v_mul_f32_e32 v39, 0x4b800000, v38
	s_nop 0
	v_cndmask_b32_e32 v38, v38, v39, vcc
	v_rsq_f32_e32 v38, v38
	s_nop 0
	v_mul_f32_e32 v39, 0x45800000, v38
	v_cndmask_b32_e32 v38, v38, v39, vcc
	v_mul_f32_e32 v38, v51, v38
	v_fma_f32 v38, v58, v38, v59
	v_fmac_f32_e32 v38, v71, v78
	v_mul_f32_e32 v38, v41, v38
	v_cvt_pk_bf16_f32 v38, v38, v38
	global_store_short v[36:37], v38, off offset:1024
	v_add_f32_dpp v36, v46, v46 quad_perm:[1,0,3,2] row_mask:0xf bank_mask:0xf bound_ctrl:1
	s_nop 1
	v_add_f32_dpp v36, v36, v36 quad_perm:[2,3,0,1] row_mask:0xf bank_mask:0xf bound_ctrl:1
	s_nop 1
	v_add_f32_dpp v36, v36, v36 row_ror:4 row_mask:0xf bank_mask:0xf bound_ctrl:1
	s_nop 1
	v_add_f32_dpp v36, v36, v36 row_ror:8 row_mask:0xf bank_mask:0xf bound_ctrl:1
	s_nop 1
	v_add_f32_dpp v36, v36, v36 row_bcast:15 row_mask:0xa bank_mask:0xf
	s_nop 1
	v_add_f32_dpp v36, v36, v36 row_bcast:31 row_mask:0xc bank_mask:0xf
	s_nop 0
	v_readlane_b32 vcc_lo, v36, 63
	s_nop 1
	v_mov_b32_e32 v36, vcc_lo
	v_fmamk_f32 v36, v36, 0xbc800000, v46
	v_mul_f32_e32 v37, v36, v36
	s_nop 1
	v_mov_b32_dpp v37, v37 quad_perm:[1,0,3,2] row_mask:0xf bank_mask:0xf bound_ctrl:1
	v_fmac_f32_e32 v37, v36, v36
	s_nop 1
	v_add_f32_dpp v37, v37, v37 quad_perm:[2,3,0,1] row_mask:0xf bank_mask:0xf bound_ctrl:1
	s_nop 1
	v_add_f32_dpp v37, v37, v37 row_ror:4 row_mask:0xf bank_mask:0xf bound_ctrl:1
	s_nop 1
	v_add_f32_dpp v37, v37, v37 row_ror:8 row_mask:0xf bank_mask:0xf bound_ctrl:1
	s_nop 1
	v_add_f32_dpp v37, v37, v37 row_bcast:15 row_mask:0xa bank_mask:0xf
	s_nop 1
	v_add_f32_dpp v37, v37, v37 row_bcast:31 row_mask:0xc bank_mask:0xf
	s_nop 0
	v_readlane_b32 vcc_lo, v37, 63
	s_nop 1
	v_mov_b32_e32 v37, vcc_lo
	v_fmamk_f32 v37, v37, 0x3c800000, v201
	v_cmp_gt_f32_e32 vcc, s83, v37
	v_mul_f32_e32 v38, 0x4b800000, v37
	s_nop 0
	v_cndmask_b32_e32 v37, v37, v38, vcc
	v_rsq_f32_e32 v37, v37
	s_nop 0
	v_mul_f32_e32 v38, 0x45800000, v37
	v_cndmask_b32_e32 v37, v37, v38, vcc
	v_mul_f32_e32 v36, v36, v37
	v_fma_f32 v38, v58, v36, v59
	ds_read2st64_b32 v[36:37], v56 offset0:32 offset1:36
	v_fmac_f32_e32 v38, v70, v79
	s_waitcnt lgkmcnt(0)
	v_mul_f32_e32 v36, v36, v38
	v_cvt_pk_bf16_f32 v36, v36, v36
	global_store_short v[34:35], v36, off offset:1024
	v_add_f32_dpp v34, v47, v47 quad_perm:[1,0,3,2] row_mask:0xf bank_mask:0xf bound_ctrl:1
	s_nop 1
	v_add_f32_dpp v34, v34, v34 quad_perm:[2,3,0,1] row_mask:0xf bank_mask:0xf bound_ctrl:1
	s_nop 1
	v_add_f32_dpp v34, v34, v34 row_ror:4 row_mask:0xf bank_mask:0xf bound_ctrl:1
	s_nop 1
	v_add_f32_dpp v34, v34, v34 row_ror:8 row_mask:0xf bank_mask:0xf bound_ctrl:1
	s_nop 1
	v_add_f32_dpp v34, v34, v34 row_bcast:15 row_mask:0xa bank_mask:0xf
	s_nop 1
	v_add_f32_dpp v34, v34, v34 row_bcast:31 row_mask:0xc bank_mask:0xf
	s_nop 0
	v_readlane_b32 vcc_lo, v34, 63
	s_nop 1
	v_mov_b32_e32 v34, vcc_lo
	v_fmac_f32_e32 v47, 0xbc800000, v34
	v_mul_f32_e32 v34, v47, v47
	s_nop 1
	v_mov_b32_dpp v34, v34 quad_perm:[1,0,3,2] row_mask:0xf bank_mask:0xf bound_ctrl:1
	v_fmac_f32_e32 v34, v47, v47
	s_nop 1
	v_add_f32_dpp v34, v34, v34 quad_perm:[2,3,0,1] row_mask:0xf bank_mask:0xf bound_ctrl:1
	s_nop 1
	v_add_f32_dpp v34, v34, v34 row_ror:4 row_mask:0xf bank_mask:0xf bound_ctrl:1
	s_nop 1
	v_add_f32_dpp v34, v34, v34 row_ror:8 row_mask:0xf bank_mask:0xf bound_ctrl:1
	s_nop 1
	v_add_f32_dpp v34, v34, v34 row_bcast:15 row_mask:0xa bank_mask:0xf
	s_nop 1
	v_add_f32_dpp v34, v34, v34 row_bcast:31 row_mask:0xc bank_mask:0xf
	s_nop 0
	v_readlane_b32 vcc_lo, v34, 63
	s_nop 1
	v_mov_b32_e32 v34, vcc_lo
	v_fmamk_f32 v34, v34, 0x3c800000, v201
	v_cmp_gt_f32_e32 vcc, s83, v34
	v_mul_f32_e32 v35, 0x4b800000, v34
	s_nop 0
	v_cndmask_b32_e32 v34, v34, v35, vcc
	v_rsq_f32_e32 v34, v34
	s_nop 0
	v_mul_f32_e32 v35, 0x45800000, v34
	v_cndmask_b32_e32 v34, v34, v35, vcc
	v_mul_f32_e32 v34, v47, v34
	v_fma_f32 v34, v58, v34, v59
	v_fmac_f32_e32 v34, v69, v80
	v_mul_f32_e32 v34, v37, v34
	v_cvt_pk_bf16_f32 v34, v34, v34
	global_store_short v[32:33], v34, off offset:1024
	v_add_f32_dpp v32, v44, v44 quad_perm:[1,0,3,2] row_mask:0xf bank_mask:0xf bound_ctrl:1
	s_nop 1
	v_add_f32_dpp v32, v32, v32 quad_perm:[2,3,0,1] row_mask:0xf bank_mask:0xf bound_ctrl:1
; __device__ __forceinline__ unsigned short f2bf(float f) { unsigned r; asm("v_cvt_pk_bf16_f32 %0, %1, %1" : "=v"(r) : "v"(f)); return (unsigned short)(r & 0xffffu); }
; __device__ __forceinline__ float wave_sum(float v) {
;   v = row16_sum(v); v += __shfl_xor(v, 16); v += __shfl_xor(v, 32);
;   return v;
; }
; __device__ __forceinline__ void rwkv_fin_item(const Params& p, int l, int item, char* ldsraw) {
;     ...
; #pragma unroll
;   for (int t = 0; t < 16; t++) {
;     const float y = yv[t];
;     const float mean = wave_sum(y) * (1.f / 64.f);
;     const float dlt = y - mean;
;     const float var = wave_sum(dlt * dlt) * (1.f / 64.f);
;     const float yn = dlt * rsqrtf(var + 64e-5f) * lw + lb;
;     const float g = lds[1024 + t * 256 + tid];
;     Y[(size_t)(tok0 + t) * 1024 + 512 + tid] = f2bf((yn + c3v[t] * vv[t]) * g);
;   }
	s_nop 1
	v_add_f32_dpp v32, v32, v32 row_ror:4 row_mask:0xf bank_mask:0xf bound_ctrl:1
	s_nop 1
	v_add_f32_dpp v32, v32, v32 row_ror:8 row_mask:0xf bank_mask:0xf bound_ctrl:1
	s_nop 1
	v_add_f32_dpp v32, v32, v32 row_bcast:15 row_mask:0xa bank_mask:0xf
	s_nop 1
	v_add_f32_dpp v32, v32, v32 row_bcast:31 row_mask:0xc bank_mask:0xf
	s_nop 0
	v_readlane_b32 vcc_lo, v32, 63
	s_nop 1
	v_mov_b32_e32 v32, vcc_lo
	v_fmamk_f32 v32, v32, 0xbc800000, v44
	v_mul_f32_e32 v33, v32, v32
	s_nop 1
	v_mov_b32_dpp v33, v33 quad_perm:[1,0,3,2] row_mask:0xf bank_mask:0xf bound_ctrl:1
	v_fmac_f32_e32 v33, v32, v32
	s_nop 1
	v_add_f32_dpp v33, v33, v33 quad_perm:[2,3,0,1] row_mask:0xf bank_mask:0xf bound_ctrl:1
	s_nop 1
	v_add_f32_dpp v33, v33, v33 row_ror:4 row_mask:0xf bank_mask:0xf bound_ctrl:1
	s_nop 1
	v_add_f32_dpp v33, v33, v33 row_ror:8 row_mask:0xf bank_mask:0xf bound_ctrl:1
	s_nop 1
	v_add_f32_dpp v33, v33, v33 row_bcast:15 row_mask:0xa bank_mask:0xf
	s_nop 1
	v_add_f32_dpp v33, v33, v33 row_bcast:31 row_mask:0xc bank_mask:0xf
	s_nop 0
	v_readlane_b32 vcc_lo, v33, 63
	s_nop 1
	v_mov_b32_e32 v33, vcc_lo
	v_fmamk_f32 v33, v33, 0x3c800000, v201
	v_cmp_gt_f32_e32 vcc, s83, v33
	v_mul_f32_e32 v34, 0x4b800000, v33
	s_nop 0
	v_cndmask_b32_e32 v33, v33, v34, vcc
	v_rsq_f32_e32 v33, v33
	s_nop 0
	v_mul_f32_e32 v34, 0x45800000, v33
	v_cndmask_b32_e32 v33, v33, v34, vcc
	v_mul_f32_e32 v32, v32, v33
	v_fma_f32 v34, v58, v32, v59
	ds_read2st64_b32 v[32:33], v56 offset0:40 offset1:44
	v_fmac_f32_e32 v34, v68, v81
	s_waitcnt lgkmcnt(0)
	v_mul_f32_e32 v32, v32, v34
	v_cvt_pk_bf16_f32 v32, v32, v32
	global_store_short v[30:31], v32, off offset:1024
	v_add_f32_dpp v30, v45, v45 quad_perm:[1,0,3,2] row_mask:0xf bank_mask:0xf bound_ctrl:1
	s_nop 1
	v_add_f32_dpp v30, v30, v30 quad_perm:[2,3,0,1] row_mask:0xf bank_mask:0xf bound_ctrl:1
	s_nop 1
	v_add_f32_dpp v30, v30, v30 row_ror:4 row_mask:0xf bank_mask:0xf bound_ctrl:1
	s_nop 1
	v_add_f32_dpp v30, v30, v30 row_ror:8 row_mask:0xf bank_mask:0xf bound_ctrl:1
	s_nop 1
	v_add_f32_dpp v30, v30, v30 row_bcast:15 row_mask:0xa bank_mask:0xf
	s_nop 1
	v_add_f32_dpp v30, v30, v30 row_bcast:31 row_mask:0xc bank_mask:0xf
	s_nop 0
	v_readlane_b32 vcc_lo, v30, 63
	s_nop 1
	v_mov_b32_e32 v30, vcc_lo
	v_fmac_f32_e32 v45, 0xbc800000, v30
	v_mul_f32_e32 v30, v45, v45
	s_nop 1
	v_mov_b32_dpp v30, v30 quad_perm:[1,0,3,2] row_mask:0xf bank_mask:0xf bound_ctrl:1
	v_fmac_f32_e32 v30, v45, v45
	s_nop 1
	v_add_f32_dpp v30, v30, v30 quad_perm:[2,3,0,1] row_mask:0xf bank_mask:0xf bound_ctrl:1
	s_nop 1
	v_add_f32_dpp v30, v30, v30 row_ror:4 row_mask:0xf bank_mask:0xf bound_ctrl:1
	s_nop 1
	v_add_f32_dpp v30, v30, v30 row_ror:8 row_mask:0xf bank_mask:0xf bound_ctrl:1
	s_nop 1
	v_add_f32_dpp v30, v30, v30 row_bcast:15 row_mask:0xa bank_mask:0xf
	s_nop 1
	v_add_f32_dpp v30, v30, v30 row_bcast:31 row_mask:0xc bank_mask:0xf
	s_nop 0
	v_readlane_b32 vcc_lo, v30, 63
	s_nop 1
	v_mov_b32_e32 v30, vcc_lo
	v_fmamk_f32 v30, v30, 0x3c800000, v201
	v_cmp_gt_f32_e32 vcc, s83, v30
	v_mul_f32_e32 v31, 0x4b800000, v30
	s_nop 0
	v_cndmask_b32_e32 v30, v30, v31, vcc
	v_rsq_f32_e32 v30, v30
	s_nop 0
	v_mul_f32_e32 v31, 0x45800000, v30
	v_cndmask_b32_e32 v30, v30, v31, vcc
	v_mul_f32_e32 v30, v45, v30
	v_fma_f32 v30, v58, v30, v59
	v_fmac_f32_e32 v30, v67, v82
	v_mul_f32_e32 v30, v33, v30
	v_cvt_pk_bf16_f32 v30, v30, v30
	global_store_short v[28:29], v30, off offset:1024
	v_add_f32_dpp v28, v10, v10 quad_perm:[1,0,3,2] row_mask:0xf bank_mask:0xf bound_ctrl:1
	s_nop 1
	v_add_f32_dpp v28, v28, v28 quad_perm:[2,3,0,1] row_mask:0xf bank_mask:0xf bound_ctrl:1
	s_nop 1
	v_add_f32_dpp v28, v28, v28 row_ror:4 row_mask:0xf bank_mask:0xf bound_ctrl:1
	s_nop 1
	v_add_f32_dpp v28, v28, v28 row_ror:8 row_mask:0xf bank_mask:0xf bound_ctrl:1
	s_nop 1
	v_add_f32_dpp v28, v28, v28 row_bcast:15 row_mask:0xa bank_mask:0xf
	s_nop 1
	v_add_f32_dpp v28, v28, v28 row_bcast:31 row_mask:0xc bank_mask:0xf
	s_nop 0
	v_readlane_b32 vcc_lo, v28, 63
	s_nop 1
	v_mov_b32_e32 v28, vcc_lo
	v_fmamk_f32 v10, v28, 0xbc800000, v10
	v_mul_f32_e32 v28, v10, v10
	s_nop 1
	v_mov_b32_dpp v28, v28 quad_perm:[1,0,3,2] row_mask:0xf bank_mask:0xf bound_ctrl:1
	v_fmac_f32_e32 v28, v10, v10
	s_nop 1
	v_add_f32_dpp v28, v28, v28 quad_perm:[2,3,0,1] row_mask:0xf bank_mask:0xf bound_ctrl:1
	s_nop 1
	v_add_f32_dpp v28, v28, v28 row_ror:4 row_mask:0xf bank_mask:0xf bound_ctrl:1
	s_nop 1
	v_add_f32_dpp v28, v28, v28 row_ror:8 row_mask:0xf bank_mask:0xf bound_ctrl:1
	s_nop 1
	v_add_f32_dpp v28, v28, v28 row_bcast:15 row_mask:0xa bank_mask:0xf
	s_nop 1
	v_add_f32_dpp v28, v28, v28 row_bcast:31 row_mask:0xc bank_mask:0xf
	s_nop 0
	v_readlane_b32 vcc_lo, v28, 63
	s_nop 1
	v_mov_b32_e32 v28, vcc_lo
	v_fmamk_f32 v28, v28, 0x3c800000, v201
	v_cmp_gt_f32_e32 vcc, s83, v28
	v_mul_f32_e32 v29, 0x4b800000, v28
	s_nop 0
	v_cndmask_b32_e32 v28, v28, v29, vcc
	v_rsq_f32_e32 v28, v28
	s_nop 0
	v_mul_f32_e32 v29, 0x45800000, v28
	v_cndmask_b32_e32 v28, v28, v29, vcc
	v_mul_f32_e32 v10, v10, v28
	ds_read2st64_b32 v[28:29], v56 offset0:48 offset1:52
	v_fma_f32 v10, v58, v10, v59
	v_fmac_f32_e32 v10, v66, v83
	s_waitcnt lgkmcnt(0)
; __device__ __forceinline__ unsigned short f2bf(float f) { unsigned r; asm("v_cvt_pk_bf16_f32 %0, %1, %1" : "=v"(r) : "v"(f)); return (unsigned short)(r & 0xffffu); }
; __device__ __forceinline__ float wave_sum(float v) {
;   v = row16_sum(v); v += __shfl_xor(v, 16); v += __shfl_xor(v, 32);
;   return v;
; }
; __device__ __forceinline__ void rwkv_fin_item(const Params& p, int l, int item, char* ldsraw) {
;     ...
; #pragma unroll
;   for (int t = 0; t < 16; t++) {
;     const float y = yv[t];
;     const float mean = wave_sum(y) * (1.f / 64.f);
;     const float dlt = y - mean;
;     const float var = wave_sum(dlt * dlt) * (1.f / 64.f);
;     const float yn = dlt * rsqrtf(var + 64e-5f) * lw + lb;
;     const float g = lds[1024 + t * 256 + tid];
;     Y[(size_t)(tok0 + t) * 1024 + 512 + tid] = f2bf((yn + c3v[t] * vv[t]) * g);
;   }
	v_mul_f32_e32 v10, v28, v10
	v_cvt_pk_bf16_f32 v10, v10, v10
	global_store_short v[26:27], v10, off offset:1024
	s_nop 0
	v_add_f32_dpp v10, v11, v11 quad_perm:[1,0,3,2] row_mask:0xf bank_mask:0xf bound_ctrl:1
	s_nop 1
	v_add_f32_dpp v10, v10, v10 quad_perm:[2,3,0,1] row_mask:0xf bank_mask:0xf bound_ctrl:1
	s_nop 1
	v_add_f32_dpp v10, v10, v10 row_ror:4 row_mask:0xf bank_mask:0xf bound_ctrl:1
	s_nop 1
	v_add_f32_dpp v10, v10, v10 row_ror:8 row_mask:0xf bank_mask:0xf bound_ctrl:1
	s_nop 1
	v_add_f32_dpp v10, v10, v10 row_bcast:15 row_mask:0xa bank_mask:0xf
	s_nop 1
	v_add_f32_dpp v10, v10, v10 row_bcast:31 row_mask:0xc bank_mask:0xf
	s_nop 0
	v_readlane_b32 vcc_lo, v10, 63
	s_nop 1
	v_mov_b32_e32 v10, vcc_lo
	v_fmac_f32_e32 v11, 0xbc800000, v10
	v_mul_f32_e32 v10, v11, v11
	s_nop 1
	v_mov_b32_dpp v10, v10 quad_perm:[1,0,3,2] row_mask:0xf bank_mask:0xf bound_ctrl:1
	v_fmac_f32_e32 v10, v11, v11
	s_nop 1
	v_add_f32_dpp v10, v10, v10 quad_perm:[2,3,0,1] row_mask:0xf bank_mask:0xf bound_ctrl:1
	s_nop 1
	v_add_f32_dpp v10, v10, v10 row_ror:4 row_mask:0xf bank_mask:0xf bound_ctrl:1
	s_nop 1
	v_add_f32_dpp v10, v10, v10 row_ror:8 row_mask:0xf bank_mask:0xf bound_ctrl:1
	s_nop 1
	v_add_f32_dpp v10, v10, v10 row_bcast:15 row_mask:0xa bank_mask:0xf
	s_nop 1
	v_add_f32_dpp v10, v10, v10 row_bcast:31 row_mask:0xc bank_mask:0xf
	s_nop 0
	v_readlane_b32 vcc_lo, v10, 63
	s_nop 1
	v_mov_b32_e32 v10, vcc_lo
	v_fmamk_f32 v10, v10, 0x3c800000, v201
	v_cmp_gt_f32_e32 vcc, s83, v10
	v_mul_f32_e32 v26, 0x4b800000, v10
	s_nop 0
	v_cndmask_b32_e32 v10, v10, v26, vcc
	v_rsq_f32_e32 v10, v10
	s_nop 0
	v_mul_f32_e32 v26, 0x45800000, v10
	v_cndmask_b32_e32 v10, v10, v26, vcc
	v_mul_f32_e32 v10, v11, v10
	v_fma_f32 v10, v58, v10, v59
	v_fmac_f32_e32 v10, v65, v84
	v_mul_f32_e32 v10, v29, v10
	v_cvt_pk_bf16_f32 v10, v10, v10
	global_store_short v[24:25], v10, off offset:1024
	s_nop 0
	v_add_f32_dpp v10, v8, v8 quad_perm:[1,0,3,2] row_mask:0xf bank_mask:0xf bound_ctrl:1
	s_nop 1
	v_add_f32_dpp v10, v10, v10 quad_perm:[2,3,0,1] row_mask:0xf bank_mask:0xf bound_ctrl:1
	s_nop 1
	v_add_f32_dpp v10, v10, v10 row_ror:4 row_mask:0xf bank_mask:0xf bound_ctrl:1
	s_nop 1
	v_add_f32_dpp v10, v10, v10 row_ror:8 row_mask:0xf bank_mask:0xf bound_ctrl:1
	s_nop 1
	v_add_f32_dpp v10, v10, v10 row_bcast:15 row_mask:0xa bank_mask:0xf
	s_nop 1
	v_add_f32_dpp v10, v10, v10 row_bcast:31 row_mask:0xc bank_mask:0xf
	s_nop 0
	v_readlane_b32 vcc_lo, v10, 63
	s_nop 1
	v_mov_b32_e32 v10, vcc_lo
	v_fmamk_f32 v8, v10, 0xbc800000, v8
	v_mul_f32_e32 v10, v8, v8
	s_nop 1
	v_mov_b32_dpp v10, v10 quad_perm:[1,0,3,2] row_mask:0xf bank_mask:0xf bound_ctrl:1
	v_fmac_f32_e32 v10, v8, v8
	s_nop 1
	v_add_f32_dpp v10, v10, v10 quad_perm:[2,3,0,1] row_mask:0xf bank_mask:0xf bound_ctrl:1
	s_nop 1
	v_add_f32_dpp v10, v10, v10 row_ror:4 row_mask:0xf bank_mask:0xf bound_ctrl:1
	s_nop 1
	v_add_f32_dpp v10, v10, v10 row_ror:8 row_mask:0xf bank_mask:0xf bound_ctrl:1
	s_nop 1
	v_add_f32_dpp v10, v10, v10 row_bcast:15 row_mask:0xa bank_mask:0xf
	s_nop 1
	v_add_f32_dpp v10, v10, v10 row_bcast:31 row_mask:0xc bank_mask:0xf
	s_nop 0
	v_readlane_b32 vcc_lo, v10, 63
	s_nop 1
	v_mov_b32_e32 v10, vcc_lo
	v_fmamk_f32 v10, v10, 0x3c800000, v201
	v_cmp_gt_f32_e32 vcc, s83, v10
	v_mul_f32_e32 v11, 0x4b800000, v10
	s_nop 0
	v_cndmask_b32_e32 v10, v10, v11, vcc
	v_rsq_f32_e32 v10, v10
	s_nop 0
	v_mul_f32_e32 v11, 0x45800000, v10
	v_cndmask_b32_e32 v10, v10, v11, vcc
	v_mul_f32_e32 v8, v8, v10
	ds_read2st64_b32 v[10:11], v56 offset0:56 offset1:60
	v_fma_f32 v8, v58, v8, v59
	v_fmac_f32_e32 v8, v64, v85
	s_waitcnt lgkmcnt(0)
	v_mul_f32_e32 v8, v10, v8
	v_cvt_pk_bf16_f32 v8, v8, v8
	global_store_short v[22:23], v8, off offset:1024
	s_nop 0
	v_add_f32_dpp v8, v9, v9 quad_perm:[1,0,3,2] row_mask:0xf bank_mask:0xf bound_ctrl:1
	s_nop 1
	v_add_f32_dpp v8, v8, v8 quad_perm:[2,3,0,1] row_mask:0xf bank_mask:0xf bound_ctrl:1
	s_nop 1
	v_add_f32_dpp v8, v8, v8 row_ror:4 row_mask:0xf bank_mask:0xf bound_ctrl:1
	s_nop 1
	v_add_f32_dpp v8, v8, v8 row_ror:8 row_mask:0xf bank_mask:0xf bound_ctrl:1
	s_nop 1
	v_add_f32_dpp v8, v8, v8 row_bcast:15 row_mask:0xa bank_mask:0xf
	s_nop 1
	v_add_f32_dpp v8, v8, v8 row_bcast:31 row_mask:0xc bank_mask:0xf
	s_nop 0
	v_readlane_b32 vcc_lo, v8, 63
	s_nop 1
	v_mov_b32_e32 v8, vcc_lo
	v_fmac_f32_e32 v9, 0xbc800000, v8
	v_mul_f32_e32 v8, v9, v9
	s_nop 1
	v_mov_b32_dpp v8, v8 quad_perm:[1,0,3,2] row_mask:0xf bank_mask:0xf bound_ctrl:1
	v_fmac_f32_e32 v8, v9, v9
	s_nop 1
	v_add_f32_dpp v8, v8, v8 quad_perm:[2,3,0,1] row_mask:0xf bank_mask:0xf bound_ctrl:1
	s_nop 1
	v_add_f32_dpp v8, v8, v8 row_ror:4 row_mask:0xf bank_mask:0xf bound_ctrl:1
	s_nop 1
	v_add_f32_dpp v8, v8, v8 row_ror:8 row_mask:0xf bank_mask:0xf bound_ctrl:1
	s_nop 1
	v_add_f32_dpp v8, v8, v8 row_bcast:15 row_mask:0xa bank_mask:0xf
	s_nop 1
	v_add_f32_dpp v8, v8, v8 row_bcast:31 row_mask:0xc bank_mask:0xf
	s_nop 0
	v_readlane_b32 vcc_lo, v8, 63
	s_nop 1
	v_mov_b32_e32 v8, vcc_lo
	v_fmamk_f32 v8, v8, 0x3c800000, v201
	v_cmp_gt_f32_e32 vcc, s83, v8
	v_mul_f32_e32 v10, 0x4b800000, v8
	s_nop 0
	v_cndmask_b32_e32 v8, v8, v10, vcc
	v_rsq_f32_e32 v8, v8
	s_nop 0
	v_mul_f32_e32 v10, 0x45800000, v8
	v_cndmask_b32_e32 v8, v8, v10, vcc
	v_mul_f32_e32 v8, v9, v8
	v_fma_f32 v8, v58, v8, v59
	v_fmac_f32_e32 v8, v63, v57
	v_mul_f32_e32 v8, v11, v8
	v_cvt_pk_bf16_f32 v8, v8, v8
	global_store_short v[20:21], v8, off offset:1024
	s_nop 0
	v_add_f32_dpp v8, v6, v6 quad_perm:[1,0,3,2] row_mask:0xf bank_mask:0xf bound_ctrl:1
	s_nop 1
	v_add_f32_dpp v8, v8, v8 quad_perm:[2,3,0,1] row_mask:0xf bank_mask:0xf bound_ctrl:1
	s_nop 1
	v_add_f32_dpp v8, v8, v8 row_ror:4 row_mask:0xf bank_mask:0xf bound_ctrl:1
; __device__ __forceinline__ unsigned short f2bf(float f) { unsigned r; asm("v_cvt_pk_bf16_f32 %0, %1, %1" : "=v"(r) : "v"(f)); return (unsigned short)(r & 0xffffu); }
; __device__ __forceinline__ float wave_sum(float v) {
;   v = row16_sum(v); v += __shfl_xor(v, 16); v += __shfl_xor(v, 32);
;   return v;
; }
; __device__ __forceinline__ void rwkv_fin_item(const Params& p, int l, int item, char* ldsraw) {
;     ...
; #pragma unroll
;   for (int t = 0; t < 16; t++) {
;     const float y = yv[t];
;     const float mean = wave_sum(y) * (1.f / 64.f);
;     const float dlt = y - mean;
;     const float var = wave_sum(dlt * dlt) * (1.f / 64.f);
;     const float yn = dlt * rsqrtf(var + 64e-5f) * lw + lb;
;     const float g = lds[1024 + t * 256 + tid];
;     Y[(size_t)(tok0 + t) * 1024 + 512 + tid] = f2bf((yn + c3v[t] * vv[t]) * g);
;   }
	s_nop 1
	v_add_f32_dpp v8, v8, v8 row_ror:8 row_mask:0xf bank_mask:0xf bound_ctrl:1
	s_nop 1
	v_add_f32_dpp v8, v8, v8 row_bcast:15 row_mask:0xa bank_mask:0xf
	s_nop 1
	v_add_f32_dpp v8, v8, v8 row_bcast:31 row_mask:0xc bank_mask:0xf
	s_nop 0
	v_readlane_b32 vcc_lo, v8, 63
	s_nop 1
	v_mov_b32_e32 v8, vcc_lo
	v_fmamk_f32 v6, v8, 0xbc800000, v6
	v_mul_f32_e32 v8, v6, v6
	s_nop 1
	v_mov_b32_dpp v8, v8 quad_perm:[1,0,3,2] row_mask:0xf bank_mask:0xf bound_ctrl:1
	v_fmac_f32_e32 v8, v6, v6
	s_nop 1
	v_add_f32_dpp v8, v8, v8 quad_perm:[2,3,0,1] row_mask:0xf bank_mask:0xf bound_ctrl:1
	s_nop 1
	v_add_f32_dpp v8, v8, v8 row_ror:4 row_mask:0xf bank_mask:0xf bound_ctrl:1
	s_nop 1
	v_add_f32_dpp v8, v8, v8 row_ror:8 row_mask:0xf bank_mask:0xf bound_ctrl:1
	s_nop 1
	v_add_f32_dpp v8, v8, v8 row_bcast:15 row_mask:0xa bank_mask:0xf
	s_nop 1
	v_add_f32_dpp v8, v8, v8 row_bcast:31 row_mask:0xc bank_mask:0xf
	s_nop 0
	v_readlane_b32 vcc_lo, v8, 63
	s_nop 1
	v_mov_b32_e32 v8, vcc_lo
	v_fmamk_f32 v8, v8, 0x3c800000, v201
	v_cmp_gt_f32_e32 vcc, s83, v8
	v_mul_f32_e32 v9, 0x4b800000, v8
	s_nop 0
	v_cndmask_b32_e32 v8, v8, v9, vcc
	v_rsq_f32_e32 v8, v8
	s_nop 0
	v_mul_f32_e32 v9, 0x45800000, v8
	v_cndmask_b32_e32 v8, v8, v9, vcc
	v_mul_f32_e32 v6, v6, v8
	ds_read2st64_b32 v[8:9], v56 offset0:64 offset1:68
	v_fma_f32 v6, v58, v6, v59
	v_fmac_f32_e32 v6, v62, v55
	s_waitcnt lgkmcnt(0)
	v_mul_f32_e32 v6, v8, v6
	v_cvt_pk_bf16_f32 v6, v6, v6
	global_store_short v[18:19], v6, off offset:1024
	s_nop 0
	v_add_f32_dpp v6, v7, v7 quad_perm:[1,0,3,2] row_mask:0xf bank_mask:0xf bound_ctrl:1
	s_nop 1
	v_add_f32_dpp v6, v6, v6 quad_perm:[2,3,0,1] row_mask:0xf bank_mask:0xf bound_ctrl:1
	s_nop 1
	v_add_f32_dpp v6, v6, v6 row_ror:4 row_mask:0xf bank_mask:0xf bound_ctrl:1
	s_nop 1
	v_add_f32_dpp v6, v6, v6 row_ror:8 row_mask:0xf bank_mask:0xf bound_ctrl:1
	s_nop 1
	v_add_f32_dpp v6, v6, v6 row_bcast:15 row_mask:0xa bank_mask:0xf
	s_nop 1
	v_add_f32_dpp v6, v6, v6 row_bcast:31 row_mask:0xc bank_mask:0xf
	s_nop 0
	v_readlane_b32 vcc_lo, v6, 63
	s_nop 1
	v_mov_b32_e32 v6, vcc_lo
	v_fmac_f32_e32 v7, 0xbc800000, v6
	v_mul_f32_e32 v6, v7, v7
	s_nop 1
	v_mov_b32_dpp v6, v6 quad_perm:[1,0,3,2] row_mask:0xf bank_mask:0xf bound_ctrl:1
	v_fmac_f32_e32 v6, v7, v7
	s_nop 1
	v_add_f32_dpp v6, v6, v6 quad_perm:[2,3,0,1] row_mask:0xf bank_mask:0xf bound_ctrl:1
	s_nop 1
	v_add_f32_dpp v6, v6, v6 row_ror:4 row_mask:0xf bank_mask:0xf bound_ctrl:1
	s_nop 1
	v_add_f32_dpp v6, v6, v6 row_ror:8 row_mask:0xf bank_mask:0xf bound_ctrl:1
	s_nop 1
	v_add_f32_dpp v6, v6, v6 row_bcast:15 row_mask:0xa bank_mask:0xf
	s_nop 1
	v_add_f32_dpp v6, v6, v6 row_bcast:31 row_mask:0xc bank_mask:0xf
	s_nop 0
	v_readlane_b32 vcc_lo, v6, 63
	s_nop 1
	v_mov_b32_e32 v6, vcc_lo
	v_fmamk_f32 v6, v6, 0x3c800000, v201
	v_cmp_gt_f32_e32 vcc, s83, v6
	v_mul_f32_e32 v8, 0x4b800000, v6
	s_nop 0
	v_cndmask_b32_e32 v6, v6, v8, vcc
	v_rsq_f32_e32 v6, v6
	s_nop 0
	v_mul_f32_e32 v8, 0x45800000, v6
	v_cndmask_b32_e32 v6, v6, v8, vcc
	v_mul_f32_e32 v6, v7, v6
	v_fma_f32 v6, v58, v6, v59
	v_fmac_f32_e32 v6, v61, v54
	v_mul_f32_e32 v6, v9, v6
	v_cvt_pk_bf16_f32 v6, v6, v6
	global_store_short v[16:17], v6, off offset:1024
	s_nop 0
	v_add_f32_dpp v6, v4, v4 quad_perm:[1,0,3,2] row_mask:0xf bank_mask:0xf bound_ctrl:1
	s_nop 1
	v_add_f32_dpp v6, v6, v6 quad_perm:[2,3,0,1] row_mask:0xf bank_mask:0xf bound_ctrl:1
	s_nop 1
	v_add_f32_dpp v6, v6, v6 row_ror:4 row_mask:0xf bank_mask:0xf bound_ctrl:1
	s_nop 1
	v_add_f32_dpp v6, v6, v6 row_ror:8 row_mask:0xf bank_mask:0xf bound_ctrl:1
	s_nop 1
	v_add_f32_dpp v6, v6, v6 row_bcast:15 row_mask:0xa bank_mask:0xf
	s_nop 1
	v_add_f32_dpp v6, v6, v6 row_bcast:31 row_mask:0xc bank_mask:0xf
	s_nop 0
	v_readlane_b32 vcc_lo, v6, 63
	s_nop 1
	v_mov_b32_e32 v6, vcc_lo
	v_fmamk_f32 v4, v6, 0xbc800000, v4
	v_mul_f32_e32 v6, v4, v4
	s_nop 1
	v_mov_b32_dpp v6, v6 quad_perm:[1,0,3,2] row_mask:0xf bank_mask:0xf bound_ctrl:1
	v_fmac_f32_e32 v6, v4, v4
	s_nop 1
	v_add_f32_dpp v6, v6, v6 quad_perm:[2,3,0,1] row_mask:0xf bank_mask:0xf bound_ctrl:1
	s_nop 1
	v_add_f32_dpp v6, v6, v6 row_ror:4 row_mask:0xf bank_mask:0xf bound_ctrl:1
	s_nop 1
	v_add_f32_dpp v6, v6, v6 row_ror:8 row_mask:0xf bank_mask:0xf bound_ctrl:1
	s_nop 1
	v_add_f32_dpp v6, v6, v6 row_bcast:15 row_mask:0xa bank_mask:0xf
	s_nop 1
	v_add_f32_dpp v6, v6, v6 row_bcast:31 row_mask:0xc bank_mask:0xf
	s_nop 0
	v_readlane_b32 vcc_lo, v6, 63
	s_nop 1
	v_mov_b32_e32 v6, vcc_lo
	v_fmamk_f32 v6, v6, 0x3c800000, v201
	v_cmp_gt_f32_e32 vcc, s83, v6
	v_mul_f32_e32 v7, 0x4b800000, v6
	s_nop 0
	v_cndmask_b32_e32 v6, v6, v7, vcc
	v_rsq_f32_e32 v6, v6
	s_nop 0
	v_mul_f32_e32 v7, 0x45800000, v6
	v_cndmask_b32_e32 v6, v6, v7, vcc
	v_mul_f32_e32 v4, v4, v6
	ds_read2st64_b32 v[6:7], v56 offset0:72 offset1:76
	v_fma_f32 v4, v58, v4, v59
	v_fmac_f32_e32 v4, v60, v49
	s_waitcnt lgkmcnt(0)
	v_mul_f32_e32 v4, v6, v4
	v_cvt_pk_bf16_f32 v4, v4, v4
	global_store_short v[14:15], v4, off offset:1024
	s_nop 0
	v_add_f32_dpp v4, v5, v5 quad_perm:[1,0,3,2] row_mask:0xf bank_mask:0xf bound_ctrl:1
	s_nop 1
	v_add_f32_dpp v4, v4, v4 quad_perm:[2,3,0,1] row_mask:0xf bank_mask:0xf bound_ctrl:1
	s_nop 1
	v_add_f32_dpp v4, v4, v4 row_ror:4 row_mask:0xf bank_mask:0xf bound_ctrl:1
	s_nop 1
	v_add_f32_dpp v4, v4, v4 row_ror:8 row_mask:0xf bank_mask:0xf bound_ctrl:1
	s_nop 1
	v_add_f32_dpp v4, v4, v4 row_bcast:15 row_mask:0xa bank_mask:0xf
	s_nop 1
	v_add_f32_dpp v4, v4, v4 row_bcast:31 row_mask:0xc bank_mask:0xf
	s_nop 0
	v_readlane_b32 vcc_lo, v4, 63
	s_nop 1
	v_mov_b32_e32 v4, vcc_lo
	v_fmac_f32_e32 v5, 0xbc800000, v4
	v_mul_f32_e32 v4, v5, v5
	s_nop 1
	v_mov_b32_dpp v4, v4 quad_perm:[1,0,3,2] row_mask:0xf bank_mask:0xf bound_ctrl:1
	v_fmac_f32_e32 v4, v5, v5
	s_nop 1
	v_add_f32_dpp v4, v4, v4 quad_perm:[2,3,0,1] row_mask:0xf bank_mask:0xf bound_ctrl:1
	s_nop 1
	v_add_f32_dpp v4, v4, v4 row_ror:4 row_mask:0xf bank_mask:0xf bound_ctrl:1
	s_nop 1
	v_add_f32_dpp v4, v4, v4 row_ror:8 row_mask:0xf bank_mask:0xf bound_ctrl:1
	ds_bpermute_b32 v6, v48, v4
	s_waitcnt lgkmcnt(0)
	v_add_f32_e32 v4, v4, v6
	ds_bpermute_b32 v2, v2, v4
	s_waitcnt lgkmcnt(0)
	v_add_f32_e32 v2, v4, v2
	v_fmamk_f32 v2, v2, 0x3c800000, v201
	v_cmp_gt_f32_e32 vcc, s83, v2
	v_mul_f32_e32 v4, 0x4b800000, v2
	s_nop 0
	v_cndmask_b32_e32 v2, v2, v4, vcc
	v_rsq_f32_e32 v2, v2
	s_nop 0
	v_mul_f32_e32 v4, 0x45800000, v2
	v_cndmask_b32_e32 v2, v2, v4, vcc
	v_mul_f32_e32 v2, v5, v2
	v_fmac_f32_e32 v59, v58, v2
	s_waitcnt vmcnt(15)
	v_fmac_f32_e32 v59, v1, v0
	v_mul_f32_e32 v0, v7, v59
	v_cvt_pk_bf16_f32 v0, v0, v0
	global_store_short v[12:13], v0, off offset:1024
	s_barrier
	s_cbranch_scc1 .LBB0_151

; __device__ __forceinline__ float bf2f(unsigned short b) { return __uint_as_float(((unsigned)b) << 16); }
; __device__ __forceinline__ unsigned short f2bf(float f) { unsigned r; asm("v_cvt_pk_bf16_f32 %0, %1, %1" : "=v"(r) : "v"(f)); return (unsigned short)(r & 0xffffu); }
; __device__ __forceinline__ float sigmoidf_(float x) { return __builtin_amdgcn_rcpf(1.0f + __expf(-x)); }
; __device__ __forceinline__ void rwkv_prep_item(const Params& p, int l, int item, char* ldsraw) {
;     ...
;   for (int t = 0; t < 16; t++) {
;     const int s = s0 + t;
;     const bf16_t* pc = stg + (t + 1) * 768; const bf16_t* pp = stg + t * 768;
;     float r = bf2f(pc[tid]), k = bf2f(pc[256 + tid]), v = bf2f(pc[512 + tid]);
;     const float rp = bf2f(pp[tid]), kp = bf2f(pp[256 + tid]), vp = bf2f(pp[512 + tid]);
;     r += (rp - r) * mur; k += (kp - k) * muk; v += (vp - v) * muv;
;     const float wl = lds[1024 + t * 256 + tid], al = lds[1024 + 4096 + t * 256 + tid];
;     const float decay = __expf(-0.6065306597126334f * sigmoidf_(wl));
;     const float a = sigmoidf_(al);
;     const float kkr = k * kkj;
;     const float ssq = wave_sum(kkr * kkr);
;     const float kk = kkr * rsqrtf(fmaxf(ssq, 1e-24f));
;     const float km = k * (1.f + (a - 1.f) * kaj);
;     const float kka = kk * a, wr = decay * r;
;     const float c1 = wave_sum(kka * r), c2 = wave_sum(km * r), c3 = wave_sum(r * km * rkj);
;     const size_t base = (size_t)(b * 4 + h) * S + s;
;     RW[base * 64 + jl] = decay;
;     bf16_t* rb = RB + base * 320;
;     rb[jl] = f2bf(kk); rb[64 + jl] = f2bf(kka); rb[128 + jl] = f2bf(km); rb[192 + jl] = f2bf(wr); rb[256 + jl] = f2bf(v);
;     if (jl == 0) { f32x4 c; c[0] = c1; c[1] = c2; c[2] = c3; c[3] = 0.f; *(f32x4*)(RC + base * 4) = c; }
;   }
.LBB0_613:
	ds_read_u16 v0, v20 offset:1536
	ds_read_u16 v1, v20 offset:2048
	ds_read_u16 v2, v20 offset:2560
	v_add_u32_e32 v25, s3, v21
	ds_read2st64_b32 v[12:13], v25 offset1:64
	s_waitcnt lgkmcnt(3)
	v_lshlrev_b32_e32 v23, 16, v0
	s_waitcnt lgkmcnt(2)
	v_lshlrev_b32_e32 v24, 16, v1
	s_waitcnt lgkmcnt(1)
	v_lshlrev_b32_e32 v22, 16, v2
	ds_read_u16 v2, v20
	ds_read_u16 v0, v20 offset:512
	s_mov_b32 s4, 0x87a8000
	s_waitcnt lgkmcnt(1)
	v_lshlrev_b32_e32 v2, 16, v2
	s_waitcnt lgkmcnt(0)
	v_lshlrev_b32_e32 v10, 16, v0
	ds_read_u16 v0, v20 offset:1024
	s_waitcnt lgkmcnt(0)
	v_lshlrev_b32_e32 v1, 16, v0
	v_sub_f32_e32 v1, v1, v22
	v_fma_f32 v27, v58, v1, v22
	v_mul_f32_e32 v1, 0xbfb8aa3b, v12
	v_exp_f32_e32 v1, v1
	v_sub_f32_e32 v0, v2, v23
	v_sub_f32_e32 v2, v10, v24
	v_fma_f32 v11, v57, v2, v24
	v_add_f32_e32 v1, 1.0, v1
	v_rcp_f32_e32 v1, v1
	v_fma_f32 v0, v56, v0, v23
	v_mul_f32_e32 v1, 0xbf1b4598, v1
	v_mul_f32_e32 v1, 0x3fb8aa3b, v1
	v_exp_f32_e32 v28, v1
	v_mul_f32_e32 v1, 0xbfb8aa3b, v13
	v_exp_f32_e32 v1, v1
	v_mul_f32_e32 v29, v0, v28
	v_add_f32_e32 v1, 1.0, v1
	v_rcp_f32_e32 v10, v1
	v_mul_f32_e32 v1, v53, v11
	v_mul_f32_e32 v2, v1, v1
	s_nop 1
	v_mov_b32_dpp v2, v2 quad_perm:[1,0,3,2] row_mask:0xf bank_mask:0xf bound_ctrl:1
	v_fmac_f32_e32 v2, v1, v1
	s_nop 1
	v_add_f32_dpp v2, v2, v2 quad_perm:[2,3,0,1] row_mask:0xf bank_mask:0xf bound_ctrl:1
	s_nop 1
	v_add_f32_dpp v2, v2, v2 row_ror:4 row_mask:0xf bank_mask:0xf bound_ctrl:1
	s_nop 1
	v_add_f32_dpp v2, v2, v2 row_ror:8 row_mask:0xf bank_mask:0xf bound_ctrl:1
	s_nop 1
	v_add_f32_dpp v2, v2, v2 row_bcast:15 row_mask:0xa bank_mask:0xf
	s_nop 1
	v_add_f32_dpp v2, v2, v2 row_bcast:31 row_mask:0xc bank_mask:0xf
	s_nop 0
	v_readlane_b32 vcc_lo, v2, 63
	s_nop 1
	v_mov_b32_e32 v2, vcc_lo
	v_max_f32_e32 v2, 0x179abe15, v2
	v_rsq_f32_e32 v2, v2
	s_nop 0
	v_mul_f32_e32 v12, v1, v2
	v_add_f32_e32 v1, -1.0, v10
	v_fma_f32 v13, v54, v1, 1.0
	v_pk_mul_f32 v[10:11], v[10:11], v[12:13]
	s_nop 0
	v_pk_mul_f32 v[14:15], v[0:1], v[10:11] op_sel_hi:[0,1]
	v_mul_f32_e32 v2, v55, v15
	s_nop 0
	v_mov_b32_dpp v16, v14 quad_perm:[1,0,3,2] row_mask:0xf bank_mask:0xf bound_ctrl:1
	v_mov_b32_dpp v17, v15 quad_perm:[1,0,3,2] row_mask:0xf bank_mask:0xf bound_ctrl:1
	v_pk_fma_f32 v[0:1], v[0:1], v[10:11], v[16:17] op_sel_hi:[0,1,1]
	v_mov_b32_dpp v2, v2 quad_perm:[1,0,3,2] row_mask:0xf bank_mask:0xf bound_ctrl:1
	v_fmac_f32_e32 v2, v55, v15
	v_mov_b32_dpp v16, v0 quad_perm:[2,3,0,1] row_mask:0xf bank_mask:0xf bound_ctrl:1
	v_mov_b32_dpp v17, v1 quad_perm:[2,3,0,1] row_mask:0xf bank_mask:0xf bound_ctrl:1
	v_pk_add_f32 v[0:1], v[0:1], v[16:17]
	v_add_f32_dpp v2, v2, v2 quad_perm:[2,3,0,1] row_mask:0xf bank_mask:0xf bound_ctrl:1
	v_lshl_add_u64 v[14:15], s[46:47], 0, v[6:7]
	v_mov_b32_dpp v16, v0 row_ror:4 row_mask:0xf bank_mask:0xf bound_ctrl:1
	v_mov_b32_dpp v17, v1 row_ror:4 row_mask:0xf bank_mask:0xf bound_ctrl:1
	v_pk_add_f32 v[0:1], v[0:1], v[16:17]
	v_add_f32_dpp v2, v2, v2 row_ror:4 row_mask:0xf bank_mask:0xf bound_ctrl:1
	v_add_co_u32_e32 v14, vcc, s4, v14
	v_mov_b32_dpp v16, v0 row_ror:8 row_mask:0xf bank_mask:0xf bound_ctrl:1
	v_mov_b32_dpp v17, v1 row_ror:8 row_mask:0xf bank_mask:0xf bound_ctrl:1
	v_pk_add_f32 v[0:1], v[0:1], v[16:17]
	v_add_f32_dpp v2, v2, v2 row_ror:8 row_mask:0xf bank_mask:0xf bound_ctrl:1
	ds_bpermute_b32 v16, v18, v0
	ds_bpermute_b32 v17, v18, v1
	ds_bpermute_b32 v13, v18, v2
	v_addc_co_u32_e32 v15, vcc, 0, v15, vcc
	global_store_dword v[14:15], v28, off
	s_waitcnt lgkmcnt(1)
	v_pk_add_f32 v[0:1], v[0:1], v[16:17]
	s_waitcnt lgkmcnt(0)
	v_add_f32_e32 v2, v2, v13
	ds_bpermute_b32 v16, v19, v0
	ds_bpermute_b32 v17, v19, v1
	ds_bpermute_b32 v26, v19, v2
	v_cvt_pk_bf16_f32 v28, v12, v12
	v_lshl_add_u64 v[12:13], s[46:47], 0, v[8:9]
	v_cvt_pk_bf16_f32 v10, v10, v10
	global_store_short v[12:13], v10, off offset:-512
	v_cvt_pk_bf16_f32 v10, v11, v11
	global_store_short v[12:13], v10, off offset:-384
	v_cvt_pk_bf16_f32 v10, v29, v29
	global_store_short v[12:13], v10, off offset:-256
	v_cvt_pk_bf16_f32 v10, v27, v27
	global_store_short v[12:13], v10, off offset:-128
	v_lshl_add_u64 v[10:11], s[46:47], 0, v[4:5]
	global_store_short v[12:13], v28, off offset:-640
	s_and_saveexec_b64 s[28:29], s[34:35]
	s_cbranch_execz .LBB0_615
	s_waitcnt lgkmcnt(1)
	v_pk_add_f32 v[0:1], v[0:1], v[16:17]
	v_add_co_u32_e32 v16, vcc, 0xbfa8000, v10
	s_waitcnt lgkmcnt(0)
	v_add_f32_e32 v2, v2, v26
	v_addc_co_u32_e32 v17, vcc, 0, v11, vcc
	global_store_dwordx4 v[16:17], v[0:3], off
